# v086 + conv tap-weight LDS reads issued before the S1 barrier (in flight during the barrier wait) + 8 unused xcv LDS reads dropped in each split second-tile gate block
# speedup vs baseline: 1.0110x; 1.0025x over previous
; #define LAS __attribute__((address_space(3)))
; DI u32x4 pack8f(const float (&f)[8]) { u32x4 r; r[0] = pk2(f[0], f[1]); r[1] = pk2(f[2], f[3]); r[2] = pk2(f[4], f[5]); r[3] = pk2(f[6], f[7]); return r; }
; DI void phase_rglru(const Params& p, unsigned char* shm) {
;     ...
;             __syncthreads();
; #pragma unroll
;             for (int j = 0; j < 3; ++j) {
;                 const int q = tid + 512 * j, cc = q % 24;
;                 float a8[8];
;                 { const f32x4 b0 = *(const LAS f32x4*)(cw + 768 + 8 * cc), b1 = *(const LAS f32x4*)(cw + 768 + 8 * cc + 4);
; #pragma unroll
;                   for (int e = 0; e < 4; ++e) { a8[e] = b0[e]; a8[4 + e] = b1[e]; } }
; #pragma unroll
;                 for (int jj = 0; jj < 4; ++jj) {
;                     float xin[8]; { const u32x4 xraw = *(const LAS u32x4*)(lds + XR + jj * TR + loff[j]); unpack8(xraw, xin); }
;                     const f32x4 w0 = *(const LAS f32x4*)(cw + jj * 192 + 8 * cc), w1 = *(const LAS f32x4*)(cw + jj * 192 + 8 * cc + 4);
; #pragma unroll
;                     for (int e = 0; e < 4; ++e) { a8[e] += w0[e] * xin[e]; a8[4 + e] += w1[e] * xin[4 + e]; }
;                 }
;                 *(LAS u32x4*)(lds + XC + loff[j]) = pack8f(a8);
;             }
.LBB0_845:
	s_waitcnt lgkmcnt(0)
	v_mul_u32_u24_e32 v205, 0xaab, v192
	v_lshrrev_b32_e32 v205, 16, v205
	v_mul_u32_u24_e32 v170, 24, v205
	v_sub_u32_e32 v170, v192, v170
	v_mul_u32_u24_e32 v205, 0x190, v205
	v_lshl_add_u32 v205, v170, 4, v205
	v_lshlrev_b32_e32 v170, 5, v170
	v_add_u32_e32 v170, 0x1f900, v170
	ds_read_b128 v[144:147], v170 offset:3072
	ds_read_b128 v[148:151], v170 offset:3088
	ds_read_b128 v[210:213], v170
	ds_read_b128 v[214:217], v170 offset:16
	ds_read_b128 v[218:221], v170 offset:768
	ds_read_b128 v[222:225], v170 offset:784
	ds_read_b128 v[226:229], v170 offset:1536
	ds_read_b128 v[230:233], v170 offset:1552
	ds_read_b128 v[234:237], v170 offset:2304
	ds_read_b128 v[238:241], v170 offset:2320
	s_barrier
	ds_read_b128 v[128:131], v205
	ds_read_b128 v[132:135], v205 offset:400
	ds_read_b128 v[136:139], v205 offset:800
	ds_read_b128 v[140:143], v205 offset:1200
	s_waitcnt lgkmcnt(3)
	v_lshlrev_b32_e32 v170, 16, v128
	v_and_b32_e32 v171, 0xffff0000, v128
	v_pk_fma_f32 v[120:121], v[210:211], v[170:171], v[144:145]
	v_lshlrev_b32_e32 v170, 16, v129
	v_and_b32_e32 v171, 0xffff0000, v129
	v_pk_fma_f32 v[122:123], v[212:213], v[170:171], v[146:147]
	v_lshlrev_b32_e32 v170, 16, v130
	v_and_b32_e32 v171, 0xffff0000, v130
	v_pk_fma_f32 v[124:125], v[214:215], v[170:171], v[148:149]
	v_lshlrev_b32_e32 v170, 16, v131
	v_and_b32_e32 v171, 0xffff0000, v131
	v_pk_fma_f32 v[126:127], v[216:217], v[170:171], v[150:151]
	s_waitcnt lgkmcnt(2)
	v_lshlrev_b32_e32 v170, 16, v132
	v_and_b32_e32 v171, 0xffff0000, v132
	v_pk_fma_f32 v[120:121], v[218:219], v[170:171], v[120:121]
	v_lshlrev_b32_e32 v170, 16, v133
	v_and_b32_e32 v171, 0xffff0000, v133
	v_pk_fma_f32 v[122:123], v[220:221], v[170:171], v[122:123]
	v_lshlrev_b32_e32 v170, 16, v134
	v_and_b32_e32 v171, 0xffff0000, v134
	v_pk_fma_f32 v[124:125], v[222:223], v[170:171], v[124:125]
	v_lshlrev_b32_e32 v170, 16, v135
	v_and_b32_e32 v171, 0xffff0000, v135
	v_pk_fma_f32 v[126:127], v[224:225], v[170:171], v[126:127]
	s_waitcnt lgkmcnt(1)
	v_lshlrev_b32_e32 v170, 16, v136
	v_and_b32_e32 v171, 0xffff0000, v136
	v_pk_fma_f32 v[120:121], v[226:227], v[170:171], v[120:121]
	v_lshlrev_b32_e32 v170, 16, v137
	v_and_b32_e32 v171, 0xffff0000, v137
	v_pk_fma_f32 v[122:123], v[228:229], v[170:171], v[122:123]
	v_lshlrev_b32_e32 v170, 16, v138
	v_and_b32_e32 v171, 0xffff0000, v138
	v_pk_fma_f32 v[124:125], v[230:231], v[170:171], v[124:125]
	v_lshlrev_b32_e32 v170, 16, v139
	v_and_b32_e32 v171, 0xffff0000, v139
	v_pk_fma_f32 v[126:127], v[232:233], v[170:171], v[126:127]
	s_waitcnt lgkmcnt(0)
	v_lshlrev_b32_e32 v170, 16, v140
	v_and_b32_e32 v171, 0xffff0000, v140
	v_pk_fma_f32 v[120:121], v[234:235], v[170:171], v[120:121]
	v_lshlrev_b32_e32 v170, 16, v141
	v_and_b32_e32 v171, 0xffff0000, v141
	v_pk_fma_f32 v[122:123], v[236:237], v[170:171], v[122:123]
	v_lshlrev_b32_e32 v170, 16, v142
	v_and_b32_e32 v171, 0xffff0000, v142
	v_pk_fma_f32 v[124:125], v[238:239], v[170:171], v[124:125]
	v_lshlrev_b32_e32 v170, 16, v143
	v_and_b32_e32 v171, 0xffff0000, v143
	v_pk_fma_f32 v[126:127], v[240:241], v[170:171], v[126:127]
	ds_read_b128 v[128:131], v205 offset:8400
	ds_read_b128 v[132:135], v205 offset:8800
	ds_read_b128 v[136:139], v205 offset:9200
	ds_read_b128 v[140:143], v205 offset:9600
	v_cvt_pk_bf16_f32 v120, v120, v121
	v_cvt_pk_bf16_f32 v121, v122, v123
	v_cvt_pk_bf16_f32 v122, v124, v125
	v_cvt_pk_bf16_f32 v123, v126, v127
	ds_write_b128 v205, v[120:123] offset:26880
	s_waitcnt lgkmcnt(4)
	v_lshlrev_b32_e32 v170, 16, v128
	v_and_b32_e32 v171, 0xffff0000, v128
	v_pk_fma_f32 v[120:121], v[210:211], v[170:171], v[144:145]
	v_lshlrev_b32_e32 v170, 16, v129
	v_and_b32_e32 v171, 0xffff0000, v129
	v_pk_fma_f32 v[122:123], v[212:213], v[170:171], v[146:147]
	v_lshlrev_b32_e32 v170, 16, v130
	v_and_b32_e32 v171, 0xffff0000, v130
	v_pk_fma_f32 v[124:125], v[214:215], v[170:171], v[148:149]
	v_lshlrev_b32_e32 v170, 16, v131
	v_and_b32_e32 v171, 0xffff0000, v131
	v_pk_fma_f32 v[126:127], v[216:217], v[170:171], v[150:151]
	s_waitcnt lgkmcnt(3)
	v_lshlrev_b32_e32 v170, 16, v132
	v_and_b32_e32 v171, 0xffff0000, v132
	v_pk_fma_f32 v[120:121], v[218:219], v[170:171], v[120:121]
	v_lshlrev_b32_e32 v170, 16, v133
	v_and_b32_e32 v171, 0xffff0000, v133
	v_pk_fma_f32 v[122:123], v[220:221], v[170:171], v[122:123]
	v_lshlrev_b32_e32 v170, 16, v134
	v_and_b32_e32 v171, 0xffff0000, v134
	v_pk_fma_f32 v[124:125], v[222:223], v[170:171], v[124:125]
	v_lshlrev_b32_e32 v170, 16, v135
	v_and_b32_e32 v171, 0xffff0000, v135
	v_pk_fma_f32 v[126:127], v[224:225], v[170:171], v[126:127]
	s_waitcnt lgkmcnt(2)
	v_lshlrev_b32_e32 v170, 16, v136
	v_and_b32_e32 v171, 0xffff0000, v136
	v_pk_fma_f32 v[120:121], v[226:227], v[170:171], v[120:121]
	v_lshlrev_b32_e32 v170, 16, v137
	v_and_b32_e32 v171, 0xffff0000, v137
	v_pk_fma_f32 v[122:123], v[228:229], v[170:171], v[122:123]
	v_lshlrev_b32_e32 v170, 16, v138
	v_and_b32_e32 v171, 0xffff0000, v138
	v_pk_fma_f32 v[124:125], v[230:231], v[170:171], v[124:125]
	v_lshlrev_b32_e32 v170, 16, v139
	v_and_b32_e32 v171, 0xffff0000, v139
	v_pk_fma_f32 v[126:127], v[232:233], v[170:171], v[126:127]
	s_waitcnt lgkmcnt(1)
	v_lshlrev_b32_e32 v170, 16, v140
	v_and_b32_e32 v171, 0xffff0000, v140
	v_pk_fma_f32 v[120:121], v[234:235], v[170:171], v[120:121]
	v_lshlrev_b32_e32 v170, 16, v141
	v_and_b32_e32 v171, 0xffff0000, v141
	v_pk_fma_f32 v[122:123], v[236:237], v[170:171], v[122:123]
	v_lshlrev_b32_e32 v170, 16, v142
	v_and_b32_e32 v171, 0xffff0000, v142
	v_pk_fma_f32 v[124:125], v[238:239], v[170:171], v[124:125]
	v_lshlrev_b32_e32 v170, 16, v143
	v_and_b32_e32 v171, 0xffff0000, v143
	v_pk_fma_f32 v[126:127], v[240:241], v[170:171], v[126:127]
	ds_read_b128 v[128:131], v205 offset:16800
	ds_read_b128 v[132:135], v205 offset:17200
	ds_read_b128 v[136:139], v205 offset:17600
	ds_read_b128 v[140:143], v205 offset:18000
	v_cvt_pk_bf16_f32 v120, v120, v121
	v_cvt_pk_bf16_f32 v121, v122, v123
	v_cvt_pk_bf16_f32 v122, v124, v125
	v_cvt_pk_bf16_f32 v123, v126, v127
	ds_write_b128 v205, v[120:123] offset:35280
	s_waitcnt lgkmcnt(4)
; #define LAS __attribute__((address_space(3)))
; DI u32x4 pack8f(const float (&f)[8]) { u32x4 r; r[0] = pk2(f[0], f[1]); r[1] = pk2(f[2], f[3]); r[2] = pk2(f[4], f[5]); r[3] = pk2(f[6], f[7]); return r; }
; DI void phase_rglru(const Params& p, unsigned char* shm) {
;     ...
; #pragma unroll
;             for (int j = 0; j < 3; ++j) {
;                 const int q = tid + 512 * j, cc = q % 24;
;                 float a8[8];
;                 { const f32x4 b0 = *(const LAS f32x4*)(cw + 768 + 8 * cc), b1 = *(const LAS f32x4*)(cw + 768 + 8 * cc + 4);
; #pragma unroll
;                   for (int e = 0; e < 4; ++e) { a8[e] = b0[e]; a8[4 + e] = b1[e]; } }
; #pragma unroll
;                 for (int jj = 0; jj < 4; ++jj) {
;                     float xin[8]; { const u32x4 xraw = *(const LAS u32x4*)(lds + XR + jj * TR + loff[j]); unpack8(xraw, xin); }
;                     const f32x4 w0 = *(const LAS f32x4*)(cw + jj * 192 + 8 * cc), w1 = *(const LAS f32x4*)(cw + jj * 192 + 8 * cc + 4);
; #pragma unroll
;                     for (int e = 0; e < 4; ++e) { a8[e] += w0[e] * xin[e]; a8[4 + e] += w1[e] * xin[4 + e]; }
;                 }
;                 *(LAS u32x4*)(lds + XC + loff[j]) = pack8f(a8);
;             }
	v_lshlrev_b32_e32 v170, 16, v128
	v_and_b32_e32 v171, 0xffff0000, v128
	v_pk_fma_f32 v[120:121], v[210:211], v[170:171], v[144:145]
	v_lshlrev_b32_e32 v170, 16, v129
	v_and_b32_e32 v171, 0xffff0000, v129
	v_pk_fma_f32 v[122:123], v[212:213], v[170:171], v[146:147]
	v_lshlrev_b32_e32 v170, 16, v130
	v_and_b32_e32 v171, 0xffff0000, v130
	v_pk_fma_f32 v[124:125], v[214:215], v[170:171], v[148:149]
	v_lshlrev_b32_e32 v170, 16, v131
	v_and_b32_e32 v171, 0xffff0000, v131
	v_pk_fma_f32 v[126:127], v[216:217], v[170:171], v[150:151]
	s_waitcnt lgkmcnt(3)
	v_lshlrev_b32_e32 v170, 16, v132
	v_and_b32_e32 v171, 0xffff0000, v132
	v_pk_fma_f32 v[120:121], v[218:219], v[170:171], v[120:121]
	v_lshlrev_b32_e32 v170, 16, v133
	v_and_b32_e32 v171, 0xffff0000, v133
	v_pk_fma_f32 v[122:123], v[220:221], v[170:171], v[122:123]
	v_lshlrev_b32_e32 v170, 16, v134
	v_and_b32_e32 v171, 0xffff0000, v134
	v_pk_fma_f32 v[124:125], v[222:223], v[170:171], v[124:125]
	v_lshlrev_b32_e32 v170, 16, v135
	v_and_b32_e32 v171, 0xffff0000, v135
	v_pk_fma_f32 v[126:127], v[224:225], v[170:171], v[126:127]
	s_waitcnt lgkmcnt(2)
	v_lshlrev_b32_e32 v170, 16, v136
	v_and_b32_e32 v171, 0xffff0000, v136
	v_pk_fma_f32 v[120:121], v[226:227], v[170:171], v[120:121]
	v_lshlrev_b32_e32 v170, 16, v137
	v_and_b32_e32 v171, 0xffff0000, v137
	v_pk_fma_f32 v[122:123], v[228:229], v[170:171], v[122:123]
	v_lshlrev_b32_e32 v170, 16, v138
	v_and_b32_e32 v171, 0xffff0000, v138
	v_pk_fma_f32 v[124:125], v[230:231], v[170:171], v[124:125]
	v_lshlrev_b32_e32 v170, 16, v139
	v_and_b32_e32 v171, 0xffff0000, v139
	v_pk_fma_f32 v[126:127], v[232:233], v[170:171], v[126:127]
	s_waitcnt lgkmcnt(1)
	v_lshlrev_b32_e32 v170, 16, v140
	v_and_b32_e32 v171, 0xffff0000, v140
	v_pk_fma_f32 v[120:121], v[234:235], v[170:171], v[120:121]
	v_lshlrev_b32_e32 v170, 16, v141
	v_and_b32_e32 v171, 0xffff0000, v141
	v_pk_fma_f32 v[122:123], v[236:237], v[170:171], v[122:123]
	v_lshlrev_b32_e32 v170, 16, v142
	v_and_b32_e32 v171, 0xffff0000, v142
	v_pk_fma_f32 v[124:125], v[238:239], v[170:171], v[124:125]
	v_lshlrev_b32_e32 v170, 16, v143
	v_and_b32_e32 v171, 0xffff0000, v143
	v_pk_fma_f32 v[126:127], v[240:241], v[170:171], v[126:127]
	v_cvt_pk_bf16_f32 v120, v120, v121
	v_cvt_pk_bf16_f32 v121, v122, v123
	v_cvt_pk_bf16_f32 v122, v124, v125
	v_cvt_pk_bf16_f32 v123, v126, v127
	ds_write_b128 v205, v[120:123] offset:43680
	v_cmp_gt_u32_e32 vcc, 24, v192
	s_and_saveexec_b64 s[2:3], vcc
	s_cbranch_execz .Lconv_x_done
	ds_read_b128 v[128:131], v205 offset:25200
	ds_read_b128 v[132:135], v205 offset:25600
	ds_read_b128 v[136:139], v205 offset:26000
	ds_read_b128 v[140:143], v205 offset:26400
	s_waitcnt lgkmcnt(3)
	v_lshlrev_b32_e32 v170, 16, v128
	v_and_b32_e32 v171, 0xffff0000, v128
	v_pk_fma_f32 v[120:121], v[210:211], v[170:171], v[144:145]
	v_lshlrev_b32_e32 v170, 16, v129
	v_and_b32_e32 v171, 0xffff0000, v129
	v_pk_fma_f32 v[122:123], v[212:213], v[170:171], v[146:147]
	v_lshlrev_b32_e32 v170, 16, v130
	v_and_b32_e32 v171, 0xffff0000, v130
	v_pk_fma_f32 v[124:125], v[214:215], v[170:171], v[148:149]
	v_lshlrev_b32_e32 v170, 16, v131
	v_and_b32_e32 v171, 0xffff0000, v131
	v_pk_fma_f32 v[126:127], v[216:217], v[170:171], v[150:151]
	s_waitcnt lgkmcnt(2)
	v_lshlrev_b32_e32 v170, 16, v132
	v_and_b32_e32 v171, 0xffff0000, v132
	v_pk_fma_f32 v[120:121], v[218:219], v[170:171], v[120:121]
	v_lshlrev_b32_e32 v170, 16, v133
	v_and_b32_e32 v171, 0xffff0000, v133
	v_pk_fma_f32 v[122:123], v[220:221], v[170:171], v[122:123]
	v_lshlrev_b32_e32 v170, 16, v134
	v_and_b32_e32 v171, 0xffff0000, v134
	v_pk_fma_f32 v[124:125], v[222:223], v[170:171], v[124:125]
	v_lshlrev_b32_e32 v170, 16, v135
	v_and_b32_e32 v171, 0xffff0000, v135
	v_pk_fma_f32 v[126:127], v[224:225], v[170:171], v[126:127]
	s_waitcnt lgkmcnt(1)
	v_lshlrev_b32_e32 v170, 16, v136
	v_and_b32_e32 v171, 0xffff0000, v136
	v_pk_fma_f32 v[120:121], v[226:227], v[170:171], v[120:121]
	v_lshlrev_b32_e32 v170, 16, v137
	v_and_b32_e32 v171, 0xffff0000, v137
	v_pk_fma_f32 v[122:123], v[228:229], v[170:171], v[122:123]
	v_lshlrev_b32_e32 v170, 16, v138
	v_and_b32_e32 v171, 0xffff0000, v138
	v_pk_fma_f32 v[124:125], v[230:231], v[170:171], v[124:125]
	v_lshlrev_b32_e32 v170, 16, v139
	v_and_b32_e32 v171, 0xffff0000, v139
	v_pk_fma_f32 v[126:127], v[232:233], v[170:171], v[126:127]
	s_waitcnt lgkmcnt(0)
	v_lshlrev_b32_e32 v170, 16, v140
	v_and_b32_e32 v171, 0xffff0000, v140
	v_pk_fma_f32 v[120:121], v[234:235], v[170:171], v[120:121]
	v_lshlrev_b32_e32 v170, 16, v141
	v_and_b32_e32 v171, 0xffff0000, v141
	v_pk_fma_f32 v[122:123], v[236:237], v[170:171], v[122:123]
	v_lshlrev_b32_e32 v170, 16, v142
	v_and_b32_e32 v171, 0xffff0000, v142
	v_pk_fma_f32 v[124:125], v[238:239], v[170:171], v[124:125]
	v_lshlrev_b32_e32 v170, 16, v143
	v_and_b32_e32 v171, 0xffff0000, v143
	v_pk_fma_f32 v[126:127], v[240:241], v[170:171], v[126:127]
	v_cvt_pk_bf16_f32 v120, v120, v121
	v_cvt_pk_bf16_f32 v121, v122, v123
	v_cvt_pk_bf16_f32 v122, v124, v125
	v_cvt_pk_bf16_f32 v123, v126, v127
	ds_write_b128 v205, v[120:123] offset:52080
; #define LAS __attribute__((address_space(3)))
; DI void phase_rglru(const Params& p, unsigned char* shm) {
;     ...
;             {
; #pragma unroll
;                 for (int u = 0; u < 2; ++u) {
;                     if (u == 1 && w >= 4) break;
;                     f32x4 acc[4][2];
; #pragma unroll
;                     for (int mt = 0; mt < 4; ++mt) { acc[mt][0] = (f32x4){0.f, 0.f, 0.f, 0.f}; acc[mt][1] = (f32x4){0.f, 0.f, 0.f, 0.f}; }
; #pragma unroll
;                     for (int kk = 0; kk < 6; ++kk)
; #pragma unroll
;                         for (int mt = 0; mt < 4; ++mt) {
;                             const bf16x8 af = *(const LAS bf16x8*)(lds + XC + (16 * mt + fr) * TR + (32 * kk + 8 * fq) * 2);
;                             acc[mt][0] = __builtin_amdgcn_mfma_f32_16x16x32_bf16(af, Bf[u][kk], acc[mt][0], 0, 0, 0);
;                             acc[mt][1] = __builtin_amdgcn_mfma_f32_16x16x32_bf16(af, Bf[2 + u][kk], acc[mt][1], 0, 0, 0);
;                         }
;                     const int ch = chb + 16 * u + fr;
;                     const float ba = gb[ch], bx = gb[192 + ch], sp = gb[384 + ch];
.Lconv_x_done:
	s_or_b64 exec, exec, s[2:3]
	s_waitcnt lgkmcnt(0)
	s_barrier
	ds_read_b128 v[120:123], v204 offset:26880
	ds_read_b128 v[124:127], v204 offset:33280
	ds_read_b128 v[128:131], v204 offset:39680
	ds_read_b128 v[132:135], v204 offset:46080
	ds_read_b128 v[226:229], v204 offset:26944
	s_waitcnt lgkmcnt(4)
	v_mfma_f32_16x16x32_bf16 v[148:151], v[120:123], v[0:3], 0
	v_mfma_f32_16x16x32_bf16 v[144:147], v[120:123], v[48:51], 0
	ds_read_b128 v[230:233], v204 offset:33344
	s_waitcnt lgkmcnt(4)
	v_mfma_f32_16x16x32_bf16 v[140:143], v[124:127], v[0:3], 0
	v_mfma_f32_16x16x32_bf16 v[136:139], v[124:127], v[48:51], 0
	ds_read_b128 v[120:123], v204 offset:39744
	s_waitcnt lgkmcnt(4)
	v_mfma_f32_16x16x32_bf16 v[214:217], v[128:131], v[0:3], 0
	v_mfma_f32_16x16x32_bf16 v[210:213], v[128:131], v[48:51], 0
	ds_read_b128 v[124:127], v204 offset:46144
	s_waitcnt lgkmcnt(4)
	v_mfma_f32_16x16x32_bf16 v[218:221], v[132:135], v[0:3], 0
	v_mfma_f32_16x16x32_bf16 v[222:225], v[132:135], v[48:51], 0
	ds_read_b128 v[128:131], v204 offset:27008
	s_waitcnt lgkmcnt(4)
	v_mfma_f32_16x16x32_bf16 v[148:151], v[226:229], v[4:7], v[148:151]
	v_mfma_f32_16x16x32_bf16 v[144:147], v[226:229], v[52:55], v[144:147]
	ds_read_b128 v[132:135], v204 offset:33408
	s_waitcnt lgkmcnt(4)
	v_mfma_f32_16x16x32_bf16 v[140:143], v[230:233], v[4:7], v[140:143]
	v_mfma_f32_16x16x32_bf16 v[136:139], v[230:233], v[52:55], v[136:139]
	ds_read_b128 v[226:229], v204 offset:39808
	s_waitcnt lgkmcnt(4)
	v_mfma_f32_16x16x32_bf16 v[214:217], v[120:123], v[4:7], v[214:217]
	v_mfma_f32_16x16x32_bf16 v[210:213], v[120:123], v[52:55], v[210:213]
	ds_read_b128 v[230:233], v204 offset:46208
	s_waitcnt lgkmcnt(4)
	v_mfma_f32_16x16x32_bf16 v[218:221], v[124:127], v[4:7], v[218:221]
	v_mfma_f32_16x16x32_bf16 v[222:225], v[124:127], v[52:55], v[222:225]
	ds_read_b128 v[120:123], v204 offset:27072
	s_waitcnt lgkmcnt(4)
	v_mfma_f32_16x16x32_bf16 v[148:151], v[128:131], v[8:11], v[148:151]
	v_mfma_f32_16x16x32_bf16 v[144:147], v[128:131], v[56:59], v[144:147]
	ds_read_b128 v[124:127], v204 offset:33472
	s_waitcnt lgkmcnt(4)
	v_mfma_f32_16x16x32_bf16 v[140:143], v[132:135], v[8:11], v[140:143]
	v_mfma_f32_16x16x32_bf16 v[136:139], v[132:135], v[56:59], v[136:139]
	ds_read_b128 v[128:131], v204 offset:39872
	s_waitcnt lgkmcnt(4)
	v_mfma_f32_16x16x32_bf16 v[214:217], v[226:229], v[8:11], v[214:217]
	v_mfma_f32_16x16x32_bf16 v[210:213], v[226:229], v[56:59], v[210:213]
	ds_read_b128 v[132:135], v204 offset:46272
	s_waitcnt lgkmcnt(4)
	v_mfma_f32_16x16x32_bf16 v[218:221], v[230:233], v[8:11], v[218:221]
	v_mfma_f32_16x16x32_bf16 v[222:225], v[230:233], v[56:59], v[222:225]
	ds_read_b128 v[226:229], v204 offset:27136
	s_waitcnt lgkmcnt(4)
	v_mfma_f32_16x16x32_bf16 v[148:151], v[120:123], v[12:15], v[148:151]
	v_mfma_f32_16x16x32_bf16 v[144:147], v[120:123], v[60:63], v[144:147]
	ds_read_b128 v[230:233], v204 offset:33536
	s_waitcnt lgkmcnt(4)
	v_mfma_f32_16x16x32_bf16 v[140:143], v[124:127], v[12:15], v[140:143]
	v_mfma_f32_16x16x32_bf16 v[136:139], v[124:127], v[60:63], v[136:139]
	ds_read_b128 v[120:123], v204 offset:39936
	s_waitcnt lgkmcnt(4)
	v_mfma_f32_16x16x32_bf16 v[214:217], v[128:131], v[12:15], v[214:217]
	v_mfma_f32_16x16x32_bf16 v[210:213], v[128:131], v[60:63], v[210:213]
	ds_read_b128 v[124:127], v204 offset:46336
	s_waitcnt lgkmcnt(4)
	v_mfma_f32_16x16x32_bf16 v[218:221], v[132:135], v[12:15], v[218:221]
	v_mfma_f32_16x16x32_bf16 v[222:225], v[132:135], v[60:63], v[222:225]
	ds_read_b128 v[128:131], v204 offset:27200
	s_waitcnt lgkmcnt(4)
	v_mfma_f32_16x16x32_bf16 v[148:151], v[226:229], v[16:19], v[148:151]
	v_mfma_f32_16x16x32_bf16 v[144:147], v[226:229], v[64:67], v[144:147]
	ds_read_b128 v[132:135], v204 offset:33600
	s_waitcnt lgkmcnt(4)
	v_mfma_f32_16x16x32_bf16 v[140:143], v[230:233], v[16:19], v[140:143]
	v_mfma_f32_16x16x32_bf16 v[136:139], v[230:233], v[64:67], v[136:139]
	s_waitcnt lgkmcnt(3)
	v_mfma_f32_16x16x32_bf16 v[214:217], v[120:123], v[16:19], v[214:217]
	v_mfma_f32_16x16x32_bf16 v[210:213], v[120:123], v[64:67], v[210:213]
	s_waitcnt lgkmcnt(2)
	v_mfma_f32_16x16x32_bf16 v[218:221], v[124:127], v[16:19], v[218:221]
	v_mfma_f32_16x16x32_bf16 v[222:225], v[124:127], v[64:67], v[222:225]
	s_waitcnt lgkmcnt(1)
	v_mfma_f32_16x16x32_bf16 v[148:151], v[128:131], v[20:23], v[148:151]
	v_mfma_f32_16x16x32_bf16 v[144:147], v[128:131], v[68:71], v[144:147]
	s_waitcnt lgkmcnt(0)
	v_mfma_f32_16x16x32_bf16 v[140:143], v[132:135], v[20:23], v[140:143]
	v_mfma_f32_16x16x32_bf16 v[136:139], v[132:135], v[68:71], v[136:139]
	ds_read_b128 v[120:123], v204 offset:40000
	s_nop 1
	ds_read_b128 v[128:131], v204 offset:46400
	ds_read2st64_b32 v[170:171], v184 offset1:3
	ds_read_b32 v205, v184 offset:1536
	ds_read_u16 v226, v194 offset:26880
	ds_read_u16 v227, v194 offset:27280
	ds_read_u16 v228, v194 offset:27680
	ds_read_u16 v229, v194 offset:28080
	ds_read_u16 v230, v194 offset:33280
	ds_read_u16 v231, v194 offset:33680
	ds_read_u16 v232, v194 offset:34080
	ds_read_u16 v233, v194 offset:34480
	ds_read_u16 v234, v194 offset:39680
	ds_read_u16 v235, v194 offset:40080
	ds_read_u16 v236, v194 offset:40480
	ds_read_u16 v237, v194 offset:40880
	ds_read_u16 v238, v194 offset:46080
	ds_read_u16 v239, v194 offset:46480
	ds_read_u16 v240, v194 offset:46880
	ds_read_u16 v241, v194 offset:47280
	s_waitcnt lgkmcnt(15)
; #define LAS __attribute__((address_space(3)))
; DI void phase_rglru(const Params& p, unsigned char* shm) {
;     ...
;                     const int ch = chb + 16 * u + fr;
;                     const float ba = gb[ch], bx = gb[192 + ch], sp = gb[384 + ch];
; #pragma unroll
;                     for (int mt = 0; mt < 4; ++mt)
; #pragma unroll
;                         for (int j = 0; j < 4; ++j) {
;                             const int t = 16 * mt + 4 * fq + j;
;                             const float ea = 1.f + __expf(fminf(-(acc[mt][0][j] + ba), 40.f)), ex = 1.f + __expf(fminf(-(acc[mt][1][j] + bx), 40.f));
;                             const float inv = __builtin_amdgcn_rcpf(ea * ex);
;                             const float r = inv * ex, ig = inv * ea;
;                             const float av = __expf(r * sp), om = 1.f - av;
;                             const float xcv = __uint_as_float((unsigned)*(const LAS bf16_t*)(lds + XC + t * TR + ch * 2) << 16);
;                             const float bt = __builtin_amdgcn_sqrtf(fmaxf(om * (1.f + av), 0.f)) * (ig * xcv);
	v_mov_b32_e32 v242, 0xbfb8aa3b
	v_mov_b32_e32 v243, 0x4266d4ca
	v_mul_f32_e32 v170, v242, v170
	v_mul_f32_e32 v171, v242, v171
	v_mul_f32_e32 v205, 0x3fb8aa3b, v205
	v_mfma_f32_16x16x32_bf16 v[124:127], v[120:123], v[20:23], v[214:217]
	v_mfma_f32_16x16x32_bf16 v[120:123], v[120:123], v[68:71], v[210:213]
	v_mfma_f32_16x16x32_bf16 v[132:135], v[128:131], v[20:23], v[218:221]
	v_mfma_f32_16x16x32_bf16 v[128:131], v[128:131], v[68:71], v[222:225]
	v_pk_fma_f32 v[148:149], v[148:149], v[242:243], v[170:171] op_sel_hi:[1,0,0]
	v_pk_fma_f32 v[144:145], v[144:145], v[242:243], v[170:171] op_sel:[0,0,1] op_sel_hi:[1,0,1]
	v_pk_fma_f32 v[150:151], v[150:151], v[242:243], v[170:171] op_sel_hi:[1,0,0]
	v_pk_fma_f32 v[146:147], v[146:147], v[242:243], v[170:171] op_sel:[0,0,1] op_sel_hi:[1,0,1]
	v_pk_fma_f32 v[140:141], v[140:141], v[242:243], v[170:171] op_sel_hi:[1,0,0]
	v_pk_fma_f32 v[136:137], v[136:137], v[242:243], v[170:171] op_sel:[0,0,1] op_sel_hi:[1,0,1]
	v_pk_fma_f32 v[142:143], v[142:143], v[242:243], v[170:171] op_sel_hi:[1,0,0]
	v_pk_fma_f32 v[138:139], v[138:139], v[242:243], v[170:171] op_sel:[0,0,1] op_sel_hi:[1,0,1]
	v_min_f32_e32 v148, v243, v148
	v_min_f32_e32 v149, v243, v149
	v_min_f32_e32 v144, v243, v144
	v_min_f32_e32 v145, v243, v145
	v_min_f32_e32 v150, v243, v150
	v_min_f32_e32 v151, v243, v151
	v_min_f32_e32 v146, v243, v146
	v_min_f32_e32 v147, v243, v147
	v_min_f32_e32 v140, v243, v140
	v_min_f32_e32 v141, v243, v141
	v_min_f32_e32 v136, v243, v136
	v_min_f32_e32 v137, v243, v137
	v_min_f32_e32 v142, v243, v142
	v_min_f32_e32 v143, v243, v143
	v_min_f32_e32 v138, v243, v138
	v_min_f32_e32 v139, v243, v139
	v_exp_f32_e32 v148, v148
	v_exp_f32_e32 v149, v149
	v_exp_f32_e32 v144, v144
	v_exp_f32_e32 v145, v145
	v_exp_f32_e32 v150, v150
	v_exp_f32_e32 v151, v151
	v_exp_f32_e32 v146, v146
	v_exp_f32_e32 v147, v147
	v_exp_f32_e32 v140, v140
	v_exp_f32_e32 v141, v141
	v_exp_f32_e32 v136, v136
	v_exp_f32_e32 v137, v137
	v_exp_f32_e32 v142, v142
	v_exp_f32_e32 v143, v143
	v_exp_f32_e32 v138, v138
	v_exp_f32_e32 v139, v139
	v_pk_add_f32 v[148:149], v[148:149], 1.0 op_sel_hi:[1,0]
	v_pk_add_f32 v[144:145], v[144:145], 1.0 op_sel_hi:[1,0]
	v_pk_add_f32 v[150:151], v[150:151], 1.0 op_sel_hi:[1,0]
	v_pk_add_f32 v[146:147], v[146:147], 1.0 op_sel_hi:[1,0]
	v_pk_add_f32 v[140:141], v[140:141], 1.0 op_sel_hi:[1,0]
	v_pk_add_f32 v[136:137], v[136:137], 1.0 op_sel_hi:[1,0]
	v_pk_add_f32 v[142:143], v[142:143], 1.0 op_sel_hi:[1,0]
	v_pk_add_f32 v[138:139], v[138:139], 1.0 op_sel_hi:[1,0]
	v_pk_mul_f32 v[210:211], v[148:149], v[144:145]
	v_pk_mul_f32 v[212:213], v[150:151], v[146:147]
	v_pk_mul_f32 v[214:215], v[140:141], v[136:137]
	v_pk_mul_f32 v[216:217], v[142:143], v[138:139]
	v_rcp_f32_e32 v210, v210
	v_rcp_f32_e32 v211, v211
	v_rcp_f32_e32 v212, v212
	v_rcp_f32_e32 v213, v213
	v_rcp_f32_e32 v214, v214
	v_rcp_f32_e32 v215, v215
	v_rcp_f32_e32 v216, v216
	v_rcp_f32_e32 v217, v217
	v_pk_mul_f32 v[144:145], v[144:145], v[210:211]
	v_pk_mul_f32 v[148:149], v[148:149], v[210:211]
	v_pk_mul_f32 v[146:147], v[146:147], v[212:213]
	v_pk_mul_f32 v[150:151], v[150:151], v[212:213]
	v_pk_mul_f32 v[136:137], v[136:137], v[214:215]
	v_pk_mul_f32 v[140:141], v[140:141], v[214:215]
	v_pk_mul_f32 v[138:139], v[138:139], v[216:217]
	v_pk_mul_f32 v[142:143], v[142:143], v[216:217]
	v_pk_mul_f32 v[144:145], v[144:145], v[204:205] op_sel:[0,1] op_sel_hi:[1,1]
	v_pk_mul_f32 v[146:147], v[146:147], v[204:205] op_sel:[0,1] op_sel_hi:[1,1]
	v_pk_mul_f32 v[136:137], v[136:137], v[204:205] op_sel:[0,1] op_sel_hi:[1,1]
	v_pk_mul_f32 v[138:139], v[138:139], v[204:205] op_sel:[0,1] op_sel_hi:[1,1]
	v_exp_f32_e32 v144, v144
	v_exp_f32_e32 v145, v145
	v_exp_f32_e32 v146, v146
	v_exp_f32_e32 v147, v147
	v_exp_f32_e32 v136, v136
	v_exp_f32_e32 v137, v137
	v_exp_f32_e32 v138, v138
	v_exp_f32_e32 v139, v139
	v_pk_add_f32 v[210:211], v[144:145], 1.0 op_sel_hi:[1,0] neg_lo:[1,0] neg_hi:[1,0]
	v_pk_add_f32 v[144:145], v[144:145], 1.0 op_sel_hi:[1,0]
	v_pk_add_f32 v[212:213], v[146:147], 1.0 op_sel_hi:[1,0] neg_lo:[1,0] neg_hi:[1,0]
	v_pk_add_f32 v[146:147], v[146:147], 1.0 op_sel_hi:[1,0]
	v_pk_add_f32 v[214:215], v[136:137], 1.0 op_sel_hi:[1,0] neg_lo:[1,0] neg_hi:[1,0]
	v_pk_add_f32 v[136:137], v[136:137], 1.0 op_sel_hi:[1,0]
	v_pk_add_f32 v[216:217], v[138:139], 1.0 op_sel_hi:[1,0] neg_lo:[1,0] neg_hi:[1,0]
	v_pk_add_f32 v[138:139], v[138:139], 1.0 op_sel_hi:[1,0]
	v_pk_mul_f32 v[144:145], v[210:211], v[144:145]
	v_pk_mul_f32 v[146:147], v[212:213], v[146:147]
	v_pk_mul_f32 v[136:137], v[214:215], v[136:137]
	v_pk_mul_f32 v[138:139], v[216:217], v[138:139]
	v_max_f32_e32 v144, 0, v144
	v_max_f32_e32 v145, 0, v145
	v_max_f32_e32 v146, 0, v146
	v_max_f32_e32 v147, 0, v147
	v_max_f32_e32 v136, 0, v136
	v_max_f32_e32 v137, 0, v137
	v_max_f32_e32 v138, 0, v138
	v_max_f32_e32 v139, 0, v139
	v_sqrt_f32_e32 v144, v144
	v_sqrt_f32_e32 v145, v145
	v_sqrt_f32_e32 v146, v146
	v_sqrt_f32_e32 v147, v147
	v_sqrt_f32_e32 v136, v136
	v_sqrt_f32_e32 v137, v137
	v_sqrt_f32_e32 v138, v138
	v_sqrt_f32_e32 v139, v139
	s_waitcnt lgkmcnt(0)
; #define LAS __attribute__((address_space(3)))
; DI unsigned pk2(float a, float b) { f32x2 v = {a, b}; bf2_t r = __builtin_convertvector(v, bf2_t); return __builtin_bit_cast(unsigned, r); }
; DI void phase_rglru(const Params& p, unsigned char* shm) {
;     ...
;                             const float ea = 1.f + __expf(fminf(-(acc[mt][0][j] + ba), 40.f)), ex = 1.f + __expf(fminf(-(acc[mt][1][j] + bx), 40.f));
;                             const float inv = __builtin_amdgcn_rcpf(ea * ex);
;                             const float r = inv * ex, ig = inv * ea;
;                             const float av = __expf(r * sp), om = 1.f - av;
;                             const float xcv = __uint_as_float((unsigned)*(const LAS bf16_t*)(lds + XC + t * TR + ch * 2) << 16);
;                             const float bt = __builtin_amdgcn_sqrtf(fmaxf(om * (1.f + av), 0.f)) * (ig * xcv);
;                             *(LAS bf16_t*)(lds + LAo + t * TR + ch * 2) = (bf16_t)(pk2(om, 0.f) & 0xffffu);
;                             *(LAS bf16_t*)(lds + BTo + t * TR + ch * 2) = (bf16_t)(pk2(bt, 0.f) & 0xffffu);
;                         }
	v_lshlrev_b32_e32 v226, 16, v226
	v_lshlrev_b32_e32 v227, 16, v227
	v_lshlrev_b32_e32 v228, 16, v228
	v_lshlrev_b32_e32 v229, 16, v229
	v_lshlrev_b32_e32 v230, 16, v230
	v_lshlrev_b32_e32 v231, 16, v231
	v_lshlrev_b32_e32 v232, 16, v232
	v_lshlrev_b32_e32 v233, 16, v233
	v_pk_mul_f32 v[148:149], v[148:149], v[226:227]
	v_pk_mul_f32 v[150:151], v[150:151], v[228:229]
	v_pk_mul_f32 v[140:141], v[140:141], v[230:231]
	v_pk_mul_f32 v[142:143], v[142:143], v[232:233]
	v_pk_mul_f32 v[148:149], v[148:149], v[144:145]
	v_pk_mul_f32 v[150:151], v[150:151], v[146:147]
	v_pk_mul_f32 v[140:141], v[140:141], v[136:137]
	v_pk_mul_f32 v[142:143], v[142:143], v[138:139]
	v_cvt_pk_bf16_f32 v210, v210, v211
	v_cvt_pk_bf16_f32 v148, v148, v149
	v_cvt_pk_bf16_f32 v212, v212, v213
	v_cvt_pk_bf16_f32 v150, v150, v151
	v_cvt_pk_bf16_f32 v214, v214, v215
	v_cvt_pk_bf16_f32 v140, v140, v141
	v_cvt_pk_bf16_f32 v216, v216, v217
	v_cvt_pk_bf16_f32 v142, v142, v143
	ds_write_b16 v195, v210
	ds_write_b16_d16_hi v195, v210 offset:400
	ds_write_b16 v196, v148
	ds_write_b16_d16_hi v196, v148 offset:400
	ds_write_b16 v195, v212 offset:800
	ds_write_b16_d16_hi v195, v212 offset:1200
	ds_write_b16 v196, v150 offset:800
	ds_write_b16_d16_hi v196, v150 offset:1200
	ds_write_b16 v195, v214 offset:6400
	ds_write_b16_d16_hi v195, v214 offset:6800
	ds_write_b16 v196, v140 offset:6400
	ds_write_b16_d16_hi v196, v140 offset:6800
	ds_write_b16 v195, v216 offset:7200
	ds_write_b16_d16_hi v195, v216 offset:7600
	ds_write_b16 v196, v142 offset:7200
	ds_write_b16_d16_hi v196, v142 offset:7600
	v_pk_fma_f32 v[124:125], v[124:125], v[242:243], v[170:171] op_sel_hi:[1,0,0]
	v_pk_fma_f32 v[120:121], v[120:121], v[242:243], v[170:171] op_sel:[0,0,1] op_sel_hi:[1,0,1]
	v_pk_fma_f32 v[126:127], v[126:127], v[242:243], v[170:171] op_sel_hi:[1,0,0]
	v_pk_fma_f32 v[122:123], v[122:123], v[242:243], v[170:171] op_sel:[0,0,1] op_sel_hi:[1,0,1]
	v_pk_fma_f32 v[132:133], v[132:133], v[242:243], v[170:171] op_sel_hi:[1,0,0]
	v_pk_fma_f32 v[128:129], v[128:129], v[242:243], v[170:171] op_sel:[0,0,1] op_sel_hi:[1,0,1]
	v_pk_fma_f32 v[134:135], v[134:135], v[242:243], v[170:171] op_sel_hi:[1,0,0]
	v_pk_fma_f32 v[130:131], v[130:131], v[242:243], v[170:171] op_sel:[0,0,1] op_sel_hi:[1,0,1]
	v_min_f32_e32 v124, v243, v124
	v_min_f32_e32 v125, v243, v125
	v_min_f32_e32 v120, v243, v120
	v_min_f32_e32 v121, v243, v121
	v_min_f32_e32 v126, v243, v126
	v_min_f32_e32 v127, v243, v127
	v_min_f32_e32 v122, v243, v122
	v_min_f32_e32 v123, v243, v123
	v_min_f32_e32 v132, v243, v132
	v_min_f32_e32 v133, v243, v133
	v_min_f32_e32 v128, v243, v128
	v_min_f32_e32 v129, v243, v129
	v_min_f32_e32 v134, v243, v134
	v_min_f32_e32 v135, v243, v135
	v_min_f32_e32 v130, v243, v130
	v_min_f32_e32 v131, v243, v131
	v_exp_f32_e32 v124, v124
	v_exp_f32_e32 v125, v125
	v_exp_f32_e32 v120, v120
	v_exp_f32_e32 v121, v121
	v_exp_f32_e32 v126, v126
	v_exp_f32_e32 v127, v127
	v_exp_f32_e32 v122, v122
	v_exp_f32_e32 v123, v123
	v_exp_f32_e32 v132, v132
	v_exp_f32_e32 v133, v133
	v_exp_f32_e32 v128, v128
	v_exp_f32_e32 v129, v129
	v_exp_f32_e32 v134, v134
	v_exp_f32_e32 v135, v135
	v_exp_f32_e32 v130, v130
	v_exp_f32_e32 v131, v131
	v_pk_add_f32 v[124:125], v[124:125], 1.0 op_sel_hi:[1,0]
	v_pk_add_f32 v[120:121], v[120:121], 1.0 op_sel_hi:[1,0]
	v_pk_add_f32 v[126:127], v[126:127], 1.0 op_sel_hi:[1,0]
	v_pk_add_f32 v[122:123], v[122:123], 1.0 op_sel_hi:[1,0]
	v_pk_add_f32 v[132:133], v[132:133], 1.0 op_sel_hi:[1,0]
	v_pk_add_f32 v[128:129], v[128:129], 1.0 op_sel_hi:[1,0]
	v_pk_add_f32 v[134:135], v[134:135], 1.0 op_sel_hi:[1,0]
	v_pk_add_f32 v[130:131], v[130:131], 1.0 op_sel_hi:[1,0]
	v_pk_mul_f32 v[210:211], v[124:125], v[120:121]
	v_pk_mul_f32 v[212:213], v[126:127], v[122:123]
	v_pk_mul_f32 v[214:215], v[132:133], v[128:129]
	v_pk_mul_f32 v[216:217], v[134:135], v[130:131]
	v_rcp_f32_e32 v210, v210
	v_rcp_f32_e32 v211, v211
	v_rcp_f32_e32 v212, v212
	v_rcp_f32_e32 v213, v213
	v_rcp_f32_e32 v214, v214
	v_rcp_f32_e32 v215, v215
	v_rcp_f32_e32 v216, v216
	v_rcp_f32_e32 v217, v217
	v_pk_mul_f32 v[120:121], v[120:121], v[210:211]
	v_pk_mul_f32 v[124:125], v[124:125], v[210:211]
	v_pk_mul_f32 v[122:123], v[122:123], v[212:213]
	v_pk_mul_f32 v[126:127], v[126:127], v[212:213]
	v_pk_mul_f32 v[128:129], v[128:129], v[214:215]
	v_pk_mul_f32 v[132:133], v[132:133], v[214:215]
	v_pk_mul_f32 v[130:131], v[130:131], v[216:217]
	v_pk_mul_f32 v[134:135], v[134:135], v[216:217]
	v_pk_mul_f32 v[120:121], v[120:121], v[204:205] op_sel:[0,1] op_sel_hi:[1,1]
	v_pk_mul_f32 v[122:123], v[122:123], v[204:205] op_sel:[0,1] op_sel_hi:[1,1]
	v_pk_mul_f32 v[128:129], v[128:129], v[204:205] op_sel:[0,1] op_sel_hi:[1,1]
	v_pk_mul_f32 v[130:131], v[130:131], v[204:205] op_sel:[0,1] op_sel_hi:[1,1]
	v_exp_f32_e32 v120, v120
	v_exp_f32_e32 v121, v121
	v_exp_f32_e32 v122, v122
	v_exp_f32_e32 v123, v123
	v_exp_f32_e32 v128, v128
	v_exp_f32_e32 v129, v129
	v_exp_f32_e32 v130, v130
	v_exp_f32_e32 v131, v131
	v_pk_add_f32 v[210:211], v[120:121], 1.0 op_sel_hi:[1,0] neg_lo:[1,0] neg_hi:[1,0]
	v_pk_add_f32 v[120:121], v[120:121], 1.0 op_sel_hi:[1,0]
	v_pk_add_f32 v[212:213], v[122:123], 1.0 op_sel_hi:[1,0] neg_lo:[1,0] neg_hi:[1,0]
	v_pk_add_f32 v[122:123], v[122:123], 1.0 op_sel_hi:[1,0]
	v_pk_add_f32 v[214:215], v[128:129], 1.0 op_sel_hi:[1,0] neg_lo:[1,0] neg_hi:[1,0]
	v_pk_add_f32 v[128:129], v[128:129], 1.0 op_sel_hi:[1,0]
	v_pk_add_f32 v[216:217], v[130:131], 1.0 op_sel_hi:[1,0] neg_lo:[1,0] neg_hi:[1,0]
	v_pk_add_f32 v[130:131], v[130:131], 1.0 op_sel_hi:[1,0]
	v_pk_mul_f32 v[120:121], v[210:211], v[120:121]
	v_pk_mul_f32 v[122:123], v[212:213], v[122:123]
; #define LAS __attribute__((address_space(3)))
; DI unsigned pk2(float a, float b) { f32x2 v = {a, b}; bf2_t r = __builtin_convertvector(v, bf2_t); return __builtin_bit_cast(unsigned, r); }
; DI void phase_rglru(const Params& p, unsigned char* shm) {
;     ...
;                     for (int kk = 0; kk < 6; ++kk)
; #pragma unroll
;                         for (int mt = 0; mt < 4; ++mt) {
;                             const bf16x8 af = *(const LAS bf16x8*)(lds + XC + (16 * mt + fr) * TR + (32 * kk + 8 * fq) * 2);
;                             acc[mt][0] = __builtin_amdgcn_mfma_f32_16x16x32_bf16(af, Bf[u][kk], acc[mt][0], 0, 0, 0);
;                             acc[mt][1] = __builtin_amdgcn_mfma_f32_16x16x32_bf16(af, Bf[2 + u][kk], acc[mt][1], 0, 0, 0);
;                         }
;                     const int ch = chb + 16 * u + fr;
;                     const float ba = gb[ch], bx = gb[192 + ch], sp = gb[384 + ch];
;     ...
;                             const float ea = 1.f + __expf(fminf(-(acc[mt][0][j] + ba), 40.f)), ex = 1.f + __expf(fminf(-(acc[mt][1][j] + bx), 40.f));
;                             const float inv = __builtin_amdgcn_rcpf(ea * ex);
;                             const float r = inv * ex, ig = inv * ea;
;                             const float av = __expf(r * sp), om = 1.f - av;
;                             const float xcv = __uint_as_float((unsigned)*(const LAS bf16_t*)(lds + XC + t * TR + ch * 2) << 16);
;                             const float bt = __builtin_amdgcn_sqrtf(fmaxf(om * (1.f + av), 0.f)) * (ig * xcv);
;                             *(LAS bf16_t*)(lds + LAo + t * TR + ch * 2) = (bf16_t)(pk2(om, 0.f) & 0xffffu);
;                             *(LAS bf16_t*)(lds + BTo + t * TR + ch * 2) = (bf16_t)(pk2(bt, 0.f) & 0xffffu);
;                         }
	v_pk_mul_f32 v[128:129], v[214:215], v[128:129]
	v_pk_mul_f32 v[130:131], v[216:217], v[130:131]
	v_max_f32_e32 v120, 0, v120
	v_max_f32_e32 v121, 0, v121
	v_max_f32_e32 v122, 0, v122
	v_max_f32_e32 v123, 0, v123
	v_max_f32_e32 v128, 0, v128
	v_max_f32_e32 v129, 0, v129
	v_max_f32_e32 v130, 0, v130
	v_max_f32_e32 v131, 0, v131
	v_sqrt_f32_e32 v120, v120
	v_sqrt_f32_e32 v121, v121
	v_sqrt_f32_e32 v122, v122
	v_sqrt_f32_e32 v123, v123
	v_sqrt_f32_e32 v128, v128
	v_sqrt_f32_e32 v129, v129
	v_sqrt_f32_e32 v130, v130
	v_sqrt_f32_e32 v131, v131
	v_lshlrev_b32_e32 v234, 16, v234
	v_lshlrev_b32_e32 v235, 16, v235
	v_lshlrev_b32_e32 v236, 16, v236
	v_lshlrev_b32_e32 v237, 16, v237
	v_lshlrev_b32_e32 v238, 16, v238
	v_lshlrev_b32_e32 v239, 16, v239
	v_lshlrev_b32_e32 v240, 16, v240
	v_lshlrev_b32_e32 v241, 16, v241
	v_pk_mul_f32 v[124:125], v[124:125], v[234:235]
	v_pk_mul_f32 v[126:127], v[126:127], v[236:237]
	v_pk_mul_f32 v[132:133], v[132:133], v[238:239]
	v_pk_mul_f32 v[134:135], v[134:135], v[240:241]
	v_pk_mul_f32 v[124:125], v[124:125], v[120:121]
	v_pk_mul_f32 v[126:127], v[126:127], v[122:123]
	v_pk_mul_f32 v[132:133], v[132:133], v[128:129]
	v_pk_mul_f32 v[134:135], v[134:135], v[130:131]
	v_cvt_pk_bf16_f32 v210, v210, v211
	v_cvt_pk_bf16_f32 v124, v124, v125
	v_cvt_pk_bf16_f32 v212, v212, v213
	v_cvt_pk_bf16_f32 v126, v126, v127
	v_cvt_pk_bf16_f32 v214, v214, v215
	v_cvt_pk_bf16_f32 v132, v132, v133
	v_cvt_pk_bf16_f32 v216, v216, v217
	v_cvt_pk_bf16_f32 v134, v134, v135
	ds_write_b16 v195, v210 offset:12800
	ds_write_b16_d16_hi v195, v210 offset:13200
	ds_write_b16 v196, v124 offset:12800
	ds_write_b16_d16_hi v196, v124 offset:13200
	ds_write_b16 v195, v212 offset:13600
	ds_write_b16_d16_hi v195, v212 offset:14000
	ds_write_b16 v196, v126 offset:13600
	ds_write_b16_d16_hi v196, v126 offset:14000
	ds_write_b16 v195, v214 offset:19200
	ds_write_b16_d16_hi v195, v214 offset:19600
	ds_write_b16 v196, v132 offset:19200
	ds_write_b16_d16_hi v196, v132 offset:19600
	ds_write_b16 v195, v216 offset:20000
	ds_write_b16_d16_hi v195, v216 offset:20400
	ds_write_b16 v196, v134 offset:20000
	ds_write_b16_d16_hi v196, v134 offset:20400
	s_andn2_b64 vcc, exec, s[12:13]
	s_cbranch_vccnz .Lgates_b
	ds_read_b128 v[120:123], v204 offset:26880
	ds_read_b128 v[124:127], v204 offset:33280
	ds_read_b128 v[128:131], v204 offset:26944
	ds_read_b128 v[132:135], v204 offset:33344
	ds_read_b128 v[226:229], v204 offset:27008
	s_waitcnt lgkmcnt(4)
	v_mfma_f32_16x16x32_bf16 v[148:151], v[120:123], v[24:27], 0
	v_mfma_f32_16x16x32_bf16 v[144:147], v[120:123], v[72:75], 0
	ds_read_b128 v[230:233], v204 offset:33408
	s_waitcnt lgkmcnt(4)
	v_mfma_f32_16x16x32_bf16 v[140:143], v[124:127], v[24:27], 0
	v_mfma_f32_16x16x32_bf16 v[136:139], v[124:127], v[72:75], 0
	ds_read_b128 v[120:123], v204 offset:27072
	s_waitcnt lgkmcnt(4)
	v_mfma_f32_16x16x32_bf16 v[148:151], v[128:131], v[28:31], v[148:151]
	v_mfma_f32_16x16x32_bf16 v[144:147], v[128:131], v[76:79], v[144:147]
	ds_read_b128 v[124:127], v204 offset:33472
	s_waitcnt lgkmcnt(4)
	v_mfma_f32_16x16x32_bf16 v[140:143], v[132:135], v[28:31], v[140:143]
	v_mfma_f32_16x16x32_bf16 v[136:139], v[132:135], v[76:79], v[136:139]
	ds_read_b128 v[128:131], v204 offset:27136
	s_waitcnt lgkmcnt(4)
	v_mfma_f32_16x16x32_bf16 v[148:151], v[226:229], v[32:35], v[148:151]
	v_mfma_f32_16x16x32_bf16 v[144:147], v[226:229], v[80:83], v[144:147]
	ds_read_b128 v[132:135], v204 offset:33536
	s_waitcnt lgkmcnt(4)
	v_mfma_f32_16x16x32_bf16 v[140:143], v[230:233], v[32:35], v[140:143]
	v_mfma_f32_16x16x32_bf16 v[136:139], v[230:233], v[80:83], v[136:139]
	ds_read_b128 v[226:229], v204 offset:27200
	s_waitcnt lgkmcnt(4)
	v_mfma_f32_16x16x32_bf16 v[148:151], v[120:123], v[36:39], v[148:151]
	v_mfma_f32_16x16x32_bf16 v[144:147], v[120:123], v[84:87], v[144:147]
	ds_read_b128 v[230:233], v204 offset:33600
	s_waitcnt lgkmcnt(4)
	v_mfma_f32_16x16x32_bf16 v[140:143], v[124:127], v[36:39], v[140:143]
	v_mfma_f32_16x16x32_bf16 v[136:139], v[124:127], v[84:87], v[136:139]
	s_waitcnt lgkmcnt(3)
	v_mfma_f32_16x16x32_bf16 v[148:151], v[128:131], v[40:43], v[148:151]
	v_mfma_f32_16x16x32_bf16 v[144:147], v[128:131], v[88:91], v[144:147]
	s_waitcnt lgkmcnt(2)
	v_mfma_f32_16x16x32_bf16 v[140:143], v[132:135], v[40:43], v[140:143]
	v_mfma_f32_16x16x32_bf16 v[136:139], v[132:135], v[88:91], v[136:139]
	s_waitcnt lgkmcnt(1)
	v_mfma_f32_16x16x32_bf16 v[148:151], v[226:229], v[44:47], v[148:151]
	v_mfma_f32_16x16x32_bf16 v[144:147], v[226:229], v[92:95], v[144:147]
	s_waitcnt lgkmcnt(0)
	v_mfma_f32_16x16x32_bf16 v[140:143], v[230:233], v[44:47], v[140:143]
	v_mfma_f32_16x16x32_bf16 v[136:139], v[230:233], v[92:95], v[136:139]
	s_nop 1
	ds_read2st64_b32 v[170:171], v185 offset1:3
	ds_read_b32 v205, v185 offset:1536
	ds_read_u16 v226, v197 offset:26880
	ds_read_u16 v227, v197 offset:27280
	ds_read_u16 v228, v197 offset:27680
	ds_read_u16 v229, v197 offset:28080
	ds_read_u16 v230, v197 offset:33280
	ds_read_u16 v231, v197 offset:33680
	ds_read_u16 v232, v197 offset:34080
	ds_read_u16 v233, v197 offset:34480
	s_waitcnt lgkmcnt(8)
; #define LAS __attribute__((address_space(3)))
; DI unsigned pk2(float a, float b) { f32x2 v = {a, b}; bf2_t r = __builtin_convertvector(v, bf2_t); return __builtin_bit_cast(unsigned, r); }
; DI void phase_rglru(const Params& p, unsigned char* shm) {
;     ...
;                     const int ch = chb + 16 * u + fr;
;                     const float ba = gb[ch], bx = gb[192 + ch], sp = gb[384 + ch];
; #pragma unroll
;                     for (int mt = 0; mt < 4; ++mt)
; #pragma unroll
;                         for (int j = 0; j < 4; ++j) {
;                             const int t = 16 * mt + 4 * fq + j;
;                             const float ea = 1.f + __expf(fminf(-(acc[mt][0][j] + ba), 40.f)), ex = 1.f + __expf(fminf(-(acc[mt][1][j] + bx), 40.f));
;                             const float inv = __builtin_amdgcn_rcpf(ea * ex);
;                             const float r = inv * ex, ig = inv * ea;
;                             const float av = __expf(r * sp), om = 1.f - av;
;                             const float xcv = __uint_as_float((unsigned)*(const LAS bf16_t*)(lds + XC + t * TR + ch * 2) << 16);
;                             const float bt = __builtin_amdgcn_sqrtf(fmaxf(om * (1.f + av), 0.f)) * (ig * xcv);
;                             *(LAS bf16_t*)(lds + LAo + t * TR + ch * 2) = (bf16_t)(pk2(om, 0.f) & 0xffffu);
;                             *(LAS bf16_t*)(lds + BTo + t * TR + ch * 2) = (bf16_t)(pk2(bt, 0.f) & 0xffffu);
;                         }
	v_mov_b32_e32 v242, 0xbfb8aa3b
	v_mov_b32_e32 v243, 0x4266d4ca
	v_mul_f32_e32 v170, v242, v170
	v_mul_f32_e32 v171, v242, v171
	v_mul_f32_e32 v205, 0x3fb8aa3b, v205
	v_pk_fma_f32 v[148:149], v[148:149], v[242:243], v[170:171] op_sel_hi:[1,0,0]
	v_pk_fma_f32 v[144:145], v[144:145], v[242:243], v[170:171] op_sel:[0,0,1] op_sel_hi:[1,0,1]
	v_pk_fma_f32 v[150:151], v[150:151], v[242:243], v[170:171] op_sel_hi:[1,0,0]
	v_pk_fma_f32 v[146:147], v[146:147], v[242:243], v[170:171] op_sel:[0,0,1] op_sel_hi:[1,0,1]
	v_pk_fma_f32 v[140:141], v[140:141], v[242:243], v[170:171] op_sel_hi:[1,0,0]
	v_pk_fma_f32 v[136:137], v[136:137], v[242:243], v[170:171] op_sel:[0,0,1] op_sel_hi:[1,0,1]
	v_pk_fma_f32 v[142:143], v[142:143], v[242:243], v[170:171] op_sel_hi:[1,0,0]
	v_pk_fma_f32 v[138:139], v[138:139], v[242:243], v[170:171] op_sel:[0,0,1] op_sel_hi:[1,0,1]
	v_min_f32_e32 v148, v243, v148
	v_min_f32_e32 v149, v243, v149
	v_min_f32_e32 v144, v243, v144
	v_min_f32_e32 v145, v243, v145
	v_min_f32_e32 v150, v243, v150
	v_min_f32_e32 v151, v243, v151
	v_min_f32_e32 v146, v243, v146
	v_min_f32_e32 v147, v243, v147
	v_min_f32_e32 v140, v243, v140
	v_min_f32_e32 v141, v243, v141
	v_min_f32_e32 v136, v243, v136
	v_min_f32_e32 v137, v243, v137
	v_min_f32_e32 v142, v243, v142
	v_min_f32_e32 v143, v243, v143
	v_min_f32_e32 v138, v243, v138
	v_min_f32_e32 v139, v243, v139
	v_exp_f32_e32 v148, v148
	v_exp_f32_e32 v149, v149
	v_exp_f32_e32 v144, v144
	v_exp_f32_e32 v145, v145
	v_exp_f32_e32 v150, v150
	v_exp_f32_e32 v151, v151
	v_exp_f32_e32 v146, v146
	v_exp_f32_e32 v147, v147
	v_exp_f32_e32 v140, v140
	v_exp_f32_e32 v141, v141
	v_exp_f32_e32 v136, v136
	v_exp_f32_e32 v137, v137
	v_exp_f32_e32 v142, v142
	v_exp_f32_e32 v143, v143
	v_exp_f32_e32 v138, v138
	v_exp_f32_e32 v139, v139
	v_pk_add_f32 v[148:149], v[148:149], 1.0 op_sel_hi:[1,0]
	v_pk_add_f32 v[144:145], v[144:145], 1.0 op_sel_hi:[1,0]
	v_pk_add_f32 v[150:151], v[150:151], 1.0 op_sel_hi:[1,0]
	v_pk_add_f32 v[146:147], v[146:147], 1.0 op_sel_hi:[1,0]
	v_pk_add_f32 v[140:141], v[140:141], 1.0 op_sel_hi:[1,0]
	v_pk_add_f32 v[136:137], v[136:137], 1.0 op_sel_hi:[1,0]
	v_pk_add_f32 v[142:143], v[142:143], 1.0 op_sel_hi:[1,0]
	v_pk_add_f32 v[138:139], v[138:139], 1.0 op_sel_hi:[1,0]
	v_pk_mul_f32 v[210:211], v[148:149], v[144:145]
	v_pk_mul_f32 v[212:213], v[150:151], v[146:147]
	v_pk_mul_f32 v[214:215], v[140:141], v[136:137]
	v_pk_mul_f32 v[216:217], v[142:143], v[138:139]
	v_rcp_f32_e32 v210, v210
	v_rcp_f32_e32 v211, v211
	v_rcp_f32_e32 v212, v212
	v_rcp_f32_e32 v213, v213
	v_rcp_f32_e32 v214, v214
	v_rcp_f32_e32 v215, v215
	v_rcp_f32_e32 v216, v216
	v_rcp_f32_e32 v217, v217
	v_pk_mul_f32 v[144:145], v[144:145], v[210:211]
	v_pk_mul_f32 v[148:149], v[148:149], v[210:211]
	v_pk_mul_f32 v[146:147], v[146:147], v[212:213]
	v_pk_mul_f32 v[150:151], v[150:151], v[212:213]
	v_pk_mul_f32 v[136:137], v[136:137], v[214:215]
	v_pk_mul_f32 v[140:141], v[140:141], v[214:215]
	v_pk_mul_f32 v[138:139], v[138:139], v[216:217]
	v_pk_mul_f32 v[142:143], v[142:143], v[216:217]
	v_pk_mul_f32 v[144:145], v[144:145], v[204:205] op_sel:[0,1] op_sel_hi:[1,1]
	v_pk_mul_f32 v[146:147], v[146:147], v[204:205] op_sel:[0,1] op_sel_hi:[1,1]
	v_pk_mul_f32 v[136:137], v[136:137], v[204:205] op_sel:[0,1] op_sel_hi:[1,1]
	v_pk_mul_f32 v[138:139], v[138:139], v[204:205] op_sel:[0,1] op_sel_hi:[1,1]
	v_exp_f32_e32 v144, v144
	v_exp_f32_e32 v145, v145
	v_exp_f32_e32 v146, v146
	v_exp_f32_e32 v147, v147
	v_exp_f32_e32 v136, v136
	v_exp_f32_e32 v137, v137
	v_exp_f32_e32 v138, v138
	v_exp_f32_e32 v139, v139
	v_pk_add_f32 v[210:211], v[144:145], 1.0 op_sel_hi:[1,0] neg_lo:[1,0] neg_hi:[1,0]
	v_pk_add_f32 v[144:145], v[144:145], 1.0 op_sel_hi:[1,0]
	v_pk_add_f32 v[212:213], v[146:147], 1.0 op_sel_hi:[1,0] neg_lo:[1,0] neg_hi:[1,0]
	v_pk_add_f32 v[146:147], v[146:147], 1.0 op_sel_hi:[1,0]
	v_pk_add_f32 v[214:215], v[136:137], 1.0 op_sel_hi:[1,0] neg_lo:[1,0] neg_hi:[1,0]
	v_pk_add_f32 v[136:137], v[136:137], 1.0 op_sel_hi:[1,0]
	v_pk_add_f32 v[216:217], v[138:139], 1.0 op_sel_hi:[1,0] neg_lo:[1,0] neg_hi:[1,0]
	v_pk_add_f32 v[138:139], v[138:139], 1.0 op_sel_hi:[1,0]
	v_pk_mul_f32 v[144:145], v[210:211], v[144:145]
	v_pk_mul_f32 v[146:147], v[212:213], v[146:147]
	v_pk_mul_f32 v[136:137], v[214:215], v[136:137]
	v_pk_mul_f32 v[138:139], v[216:217], v[138:139]
	v_max_f32_e32 v144, 0, v144
	v_max_f32_e32 v145, 0, v145
	v_max_f32_e32 v146, 0, v146
	v_max_f32_e32 v147, 0, v147
	v_max_f32_e32 v136, 0, v136
	v_max_f32_e32 v137, 0, v137
	v_max_f32_e32 v138, 0, v138
	v_max_f32_e32 v139, 0, v139
	v_sqrt_f32_e32 v144, v144
	v_sqrt_f32_e32 v145, v145
	v_sqrt_f32_e32 v146, v146
	v_sqrt_f32_e32 v147, v147
	v_sqrt_f32_e32 v136, v136
	v_sqrt_f32_e32 v137, v137
	v_sqrt_f32_e32 v138, v138
	v_sqrt_f32_e32 v139, v139
	s_waitcnt lgkmcnt(0)
	v_lshlrev_b32_e32 v226, 16, v226
	v_lshlrev_b32_e32 v227, 16, v227
	v_lshlrev_b32_e32 v228, 16, v228
	v_lshlrev_b32_e32 v229, 16, v229
	v_lshlrev_b32_e32 v230, 16, v230
	v_lshlrev_b32_e32 v231, 16, v231
	v_lshlrev_b32_e32 v232, 16, v232
	v_lshlrev_b32_e32 v233, 16, v233
	v_pk_mul_f32 v[148:149], v[148:149], v[226:227]
	v_pk_mul_f32 v[150:151], v[150:151], v[228:229]
	v_pk_mul_f32 v[140:141], v[140:141], v[230:231]
	v_pk_mul_f32 v[142:143], v[142:143], v[232:233]
	v_pk_mul_f32 v[148:149], v[148:149], v[144:145]
	v_pk_mul_f32 v[150:151], v[150:151], v[146:147]
	v_pk_mul_f32 v[140:141], v[140:141], v[136:137]
	v_pk_mul_f32 v[142:143], v[142:143], v[138:139]
	v_cvt_pk_bf16_f32 v210, v210, v211
	v_cvt_pk_bf16_f32 v148, v148, v149
	v_cvt_pk_bf16_f32 v212, v212, v213
	v_cvt_pk_bf16_f32 v150, v150, v151
	v_cvt_pk_bf16_f32 v214, v214, v215
	v_cvt_pk_bf16_f32 v140, v140, v141
	v_cvt_pk_bf16_f32 v216, v216, v217
	v_cvt_pk_bf16_f32 v142, v142, v143
	ds_write_b16 v198, v210
	ds_write_b16_d16_hi v198, v210 offset:400
	ds_write_b16 v199, v148
	ds_write_b16_d16_hi v199, v148 offset:400
	ds_write_b16 v198, v212 offset:800
	ds_write_b16_d16_hi v198, v212 offset:1200
	ds_write_b16 v199, v150 offset:800
	ds_write_b16_d16_hi v199, v150 offset:1200
	ds_write_b16 v198, v214 offset:6400
	ds_write_b16_d16_hi v198, v214 offset:6800
	ds_write_b16 v199, v140 offset:6400
	ds_write_b16_d16_hi v199, v140 offset:6800
	ds_write_b16 v198, v216 offset:7200
	ds_write_b16_d16_hi v198, v216 offset:7600
	ds_write_b16 v199, v142 offset:7200
	ds_write_b16_d16_hi v199, v142 offset:7600
	s_branch .LBB0_847
; #define LAS __attribute__((address_space(3)))
; DI void phase_rglru(const Params& p, unsigned char* shm) {
;     ...
;                     for (int kk = 0; kk < 6; ++kk)
; #pragma unroll
;                         for (int mt = 0; mt < 4; ++mt) {
;                             const bf16x8 af = *(const LAS bf16x8*)(lds + XC + (16 * mt + fr) * TR + (32 * kk + 8 * fq) * 2);
;                             acc[mt][0] = __builtin_amdgcn_mfma_f32_16x16x32_bf16(af, Bf[u][kk], acc[mt][0], 0, 0, 0);
;                             acc[mt][1] = __builtin_amdgcn_mfma_f32_16x16x32_bf16(af, Bf[2 + u][kk], acc[mt][1], 0, 0, 0);
;                         }
;                     const int ch = chb + 16 * u + fr;
;                     const float ba = gb[ch], bx = gb[192 + ch], sp = gb[384 + ch];
; #pragma unroll
;                     for (int mt = 0; mt < 4; ++mt)
; #pragma unroll
;                         for (int j = 0; j < 4; ++j) {
;                             const int t = 16 * mt + 4 * fq + j;
;                             const float ea = 1.f + __expf(fminf(-(acc[mt][0][j] + ba), 40.f)), ex = 1.f + __expf(fminf(-(acc[mt][1][j] + bx), 40.f));
;                             const float inv = __builtin_amdgcn_rcpf(ea * ex);
;                             const float r = inv * ex, ig = inv * ea;
;                             const float av = __expf(r * sp), om = 1.f - av;
;                             const float xcv = __uint_as_float((unsigned)*(const LAS bf16_t*)(lds + XC + t * TR + ch * 2) << 16);
.Lgates_b:
	ds_read_b128 v[120:123], v204 offset:39680
	ds_read_b128 v[124:127], v204 offset:46080
	ds_read_b128 v[128:131], v204 offset:39744
	ds_read_b128 v[132:135], v204 offset:46144
	ds_read_b128 v[226:229], v204 offset:39808
	s_waitcnt lgkmcnt(4)
	v_mfma_f32_16x16x32_bf16 v[214:217], v[120:123], v[24:27], 0
	v_mfma_f32_16x16x32_bf16 v[210:213], v[120:123], v[72:75], 0
	ds_read_b128 v[230:233], v204 offset:46208
	s_waitcnt lgkmcnt(4)
	v_mfma_f32_16x16x32_bf16 v[218:221], v[124:127], v[24:27], 0
	v_mfma_f32_16x16x32_bf16 v[222:225], v[124:127], v[72:75], 0
	ds_read_b128 v[120:123], v204 offset:39872
	s_waitcnt lgkmcnt(4)
	v_mfma_f32_16x16x32_bf16 v[214:217], v[128:131], v[28:31], v[214:217]
	v_mfma_f32_16x16x32_bf16 v[210:213], v[128:131], v[76:79], v[210:213]
	ds_read_b128 v[124:127], v204 offset:46272
	s_waitcnt lgkmcnt(4)
	v_mfma_f32_16x16x32_bf16 v[218:221], v[132:135], v[28:31], v[218:221]
	v_mfma_f32_16x16x32_bf16 v[222:225], v[132:135], v[76:79], v[222:225]
	ds_read_b128 v[128:131], v204 offset:39936
	s_waitcnt lgkmcnt(4)
	v_mfma_f32_16x16x32_bf16 v[214:217], v[226:229], v[32:35], v[214:217]
	v_mfma_f32_16x16x32_bf16 v[210:213], v[226:229], v[80:83], v[210:213]
	ds_read_b128 v[132:135], v204 offset:46336
	s_waitcnt lgkmcnt(4)
	v_mfma_f32_16x16x32_bf16 v[218:221], v[230:233], v[32:35], v[218:221]
	v_mfma_f32_16x16x32_bf16 v[222:225], v[230:233], v[80:83], v[222:225]
	s_waitcnt lgkmcnt(3)
	v_mfma_f32_16x16x32_bf16 v[214:217], v[120:123], v[36:39], v[214:217]
	v_mfma_f32_16x16x32_bf16 v[210:213], v[120:123], v[84:87], v[210:213]
	s_waitcnt lgkmcnt(2)
	v_mfma_f32_16x16x32_bf16 v[218:221], v[124:127], v[36:39], v[218:221]
	v_mfma_f32_16x16x32_bf16 v[222:225], v[124:127], v[84:87], v[222:225]
	s_waitcnt lgkmcnt(1)
	v_mfma_f32_16x16x32_bf16 v[214:217], v[128:131], v[40:43], v[214:217]
	v_mfma_f32_16x16x32_bf16 v[210:213], v[128:131], v[88:91], v[210:213]
	s_waitcnt lgkmcnt(0)
	v_mfma_f32_16x16x32_bf16 v[218:221], v[132:135], v[40:43], v[218:221]
	v_mfma_f32_16x16x32_bf16 v[222:225], v[132:135], v[88:91], v[222:225]
	ds_read_b128 v[120:123], v204 offset:40000
	s_nop 1
	ds_read_b128 v[128:131], v204 offset:46400
	ds_read2st64_b32 v[170:171], v185 offset1:3
	ds_read_b32 v205, v185 offset:1536
	ds_read_u16 v234, v197 offset:39680
	ds_read_u16 v235, v197 offset:40080
	ds_read_u16 v236, v197 offset:40480
	ds_read_u16 v237, v197 offset:40880
	ds_read_u16 v238, v197 offset:46080
	ds_read_u16 v239, v197 offset:46480
	ds_read_u16 v240, v197 offset:46880
	ds_read_u16 v241, v197 offset:47280
	s_waitcnt lgkmcnt(8)
; #define LAS __attribute__((address_space(3)))
; DI unsigned pk2(float a, float b) { f32x2 v = {a, b}; bf2_t r = __builtin_convertvector(v, bf2_t); return __builtin_bit_cast(unsigned, r); }
; DI void phase_rglru(const Params& p, unsigned char* shm) {
;     ...
;                     const int ch = chb + 16 * u + fr;
;                     const float ba = gb[ch], bx = gb[192 + ch], sp = gb[384 + ch];
; #pragma unroll
;                     for (int mt = 0; mt < 4; ++mt)
; #pragma unroll
;                         for (int j = 0; j < 4; ++j) {
;                             const int t = 16 * mt + 4 * fq + j;
;                             const float ea = 1.f + __expf(fminf(-(acc[mt][0][j] + ba), 40.f)), ex = 1.f + __expf(fminf(-(acc[mt][1][j] + bx), 40.f));
;                             const float inv = __builtin_amdgcn_rcpf(ea * ex);
;                             const float r = inv * ex, ig = inv * ea;
;                             const float av = __expf(r * sp), om = 1.f - av;
;                             const float xcv = __uint_as_float((unsigned)*(const LAS bf16_t*)(lds + XC + t * TR + ch * 2) << 16);
;                             const float bt = __builtin_amdgcn_sqrtf(fmaxf(om * (1.f + av), 0.f)) * (ig * xcv);
;                             *(LAS bf16_t*)(lds + LAo + t * TR + ch * 2) = (bf16_t)(pk2(om, 0.f) & 0xffffu);
;                             *(LAS bf16_t*)(lds + BTo + t * TR + ch * 2) = (bf16_t)(pk2(bt, 0.f) & 0xffffu);
;                         }
	v_mov_b32_e32 v242, 0xbfb8aa3b
	v_mov_b32_e32 v243, 0x4266d4ca
	v_mul_f32_e32 v170, v242, v170
	v_mul_f32_e32 v171, v242, v171
	v_mul_f32_e32 v205, 0x3fb8aa3b, v205
	v_mfma_f32_16x16x32_bf16 v[124:127], v[120:123], v[44:47], v[214:217]
	v_mfma_f32_16x16x32_bf16 v[120:123], v[120:123], v[92:95], v[210:213]
	v_mfma_f32_16x16x32_bf16 v[132:135], v[128:131], v[44:47], v[218:221]
	v_mfma_f32_16x16x32_bf16 v[128:131], v[128:131], v[92:95], v[222:225]
	s_nop 8
	v_pk_fma_f32 v[124:125], v[124:125], v[242:243], v[170:171] op_sel_hi:[1,0,0]
	v_pk_fma_f32 v[120:121], v[120:121], v[242:243], v[170:171] op_sel:[0,0,1] op_sel_hi:[1,0,1]
	v_pk_fma_f32 v[126:127], v[126:127], v[242:243], v[170:171] op_sel_hi:[1,0,0]
	v_pk_fma_f32 v[122:123], v[122:123], v[242:243], v[170:171] op_sel:[0,0,1] op_sel_hi:[1,0,1]
	v_pk_fma_f32 v[132:133], v[132:133], v[242:243], v[170:171] op_sel_hi:[1,0,0]
	v_pk_fma_f32 v[128:129], v[128:129], v[242:243], v[170:171] op_sel:[0,0,1] op_sel_hi:[1,0,1]
	v_pk_fma_f32 v[134:135], v[134:135], v[242:243], v[170:171] op_sel_hi:[1,0,0]
	v_pk_fma_f32 v[130:131], v[130:131], v[242:243], v[170:171] op_sel:[0,0,1] op_sel_hi:[1,0,1]
	v_min_f32_e32 v124, v243, v124
	v_min_f32_e32 v125, v243, v125
	v_min_f32_e32 v120, v243, v120
	v_min_f32_e32 v121, v243, v121
	v_min_f32_e32 v126, v243, v126
	v_min_f32_e32 v127, v243, v127
	v_min_f32_e32 v122, v243, v122
	v_min_f32_e32 v123, v243, v123
	v_min_f32_e32 v132, v243, v132
	v_min_f32_e32 v133, v243, v133
	v_min_f32_e32 v128, v243, v128
	v_min_f32_e32 v129, v243, v129
	v_min_f32_e32 v134, v243, v134
	v_min_f32_e32 v135, v243, v135
	v_min_f32_e32 v130, v243, v130
	v_min_f32_e32 v131, v243, v131
	v_exp_f32_e32 v124, v124
	v_exp_f32_e32 v125, v125
	v_exp_f32_e32 v120, v120
	v_exp_f32_e32 v121, v121
	v_exp_f32_e32 v126, v126
	v_exp_f32_e32 v127, v127
	v_exp_f32_e32 v122, v122
	v_exp_f32_e32 v123, v123
	v_exp_f32_e32 v132, v132
	v_exp_f32_e32 v133, v133
	v_exp_f32_e32 v128, v128
	v_exp_f32_e32 v129, v129
	v_exp_f32_e32 v134, v134
	v_exp_f32_e32 v135, v135
	v_exp_f32_e32 v130, v130
	v_exp_f32_e32 v131, v131
	v_pk_add_f32 v[124:125], v[124:125], 1.0 op_sel_hi:[1,0]
	v_pk_add_f32 v[120:121], v[120:121], 1.0 op_sel_hi:[1,0]
	v_pk_add_f32 v[126:127], v[126:127], 1.0 op_sel_hi:[1,0]
	v_pk_add_f32 v[122:123], v[122:123], 1.0 op_sel_hi:[1,0]
	v_pk_add_f32 v[132:133], v[132:133], 1.0 op_sel_hi:[1,0]
	v_pk_add_f32 v[128:129], v[128:129], 1.0 op_sel_hi:[1,0]
	v_pk_add_f32 v[134:135], v[134:135], 1.0 op_sel_hi:[1,0]
	v_pk_add_f32 v[130:131], v[130:131], 1.0 op_sel_hi:[1,0]
	v_pk_mul_f32 v[210:211], v[124:125], v[120:121]
	v_pk_mul_f32 v[212:213], v[126:127], v[122:123]
	v_pk_mul_f32 v[214:215], v[132:133], v[128:129]
	v_pk_mul_f32 v[216:217], v[134:135], v[130:131]
	v_rcp_f32_e32 v210, v210
	v_rcp_f32_e32 v211, v211
	v_rcp_f32_e32 v212, v212
	v_rcp_f32_e32 v213, v213
	v_rcp_f32_e32 v214, v214
	v_rcp_f32_e32 v215, v215
	v_rcp_f32_e32 v216, v216
	v_rcp_f32_e32 v217, v217
	v_pk_mul_f32 v[120:121], v[120:121], v[210:211]
	v_pk_mul_f32 v[124:125], v[124:125], v[210:211]
	v_pk_mul_f32 v[122:123], v[122:123], v[212:213]
	v_pk_mul_f32 v[126:127], v[126:127], v[212:213]
	v_pk_mul_f32 v[128:129], v[128:129], v[214:215]
	v_pk_mul_f32 v[132:133], v[132:133], v[214:215]
	v_pk_mul_f32 v[130:131], v[130:131], v[216:217]
	v_pk_mul_f32 v[134:135], v[134:135], v[216:217]
	v_pk_mul_f32 v[120:121], v[120:121], v[204:205] op_sel:[0,1] op_sel_hi:[1,1]
	v_pk_mul_f32 v[122:123], v[122:123], v[204:205] op_sel:[0,1] op_sel_hi:[1,1]
	v_pk_mul_f32 v[128:129], v[128:129], v[204:205] op_sel:[0,1] op_sel_hi:[1,1]
	v_pk_mul_f32 v[130:131], v[130:131], v[204:205] op_sel:[0,1] op_sel_hi:[1,1]
	v_exp_f32_e32 v120, v120
	v_exp_f32_e32 v121, v121
	v_exp_f32_e32 v122, v122
	v_exp_f32_e32 v123, v123
	v_exp_f32_e32 v128, v128
	v_exp_f32_e32 v129, v129
	v_exp_f32_e32 v130, v130
	v_exp_f32_e32 v131, v131
	v_pk_add_f32 v[210:211], v[120:121], 1.0 op_sel_hi:[1,0] neg_lo:[1,0] neg_hi:[1,0]
	v_pk_add_f32 v[120:121], v[120:121], 1.0 op_sel_hi:[1,0]
	v_pk_add_f32 v[212:213], v[122:123], 1.0 op_sel_hi:[1,0] neg_lo:[1,0] neg_hi:[1,0]
	v_pk_add_f32 v[122:123], v[122:123], 1.0 op_sel_hi:[1,0]
	v_pk_add_f32 v[214:215], v[128:129], 1.0 op_sel_hi:[1,0] neg_lo:[1,0] neg_hi:[1,0]
	v_pk_add_f32 v[128:129], v[128:129], 1.0 op_sel_hi:[1,0]
	v_pk_add_f32 v[216:217], v[130:131], 1.0 op_sel_hi:[1,0] neg_lo:[1,0] neg_hi:[1,0]
	v_pk_add_f32 v[130:131], v[130:131], 1.0 op_sel_hi:[1,0]
	v_pk_mul_f32 v[120:121], v[210:211], v[120:121]
	v_pk_mul_f32 v[122:123], v[212:213], v[122:123]
	v_pk_mul_f32 v[128:129], v[214:215], v[128:129]
	v_pk_mul_f32 v[130:131], v[216:217], v[130:131]
	v_max_f32_e32 v120, 0, v120
	v_max_f32_e32 v121, 0, v121
	v_max_f32_e32 v122, 0, v122
	v_max_f32_e32 v123, 0, v123
	v_max_f32_e32 v128, 0, v128
	v_max_f32_e32 v129, 0, v129
	v_max_f32_e32 v130, 0, v130
	v_max_f32_e32 v131, 0, v131
	v_sqrt_f32_e32 v120, v120
	v_sqrt_f32_e32 v121, v121
	v_sqrt_f32_e32 v122, v122
	v_sqrt_f32_e32 v123, v123
	v_sqrt_f32_e32 v128, v128
	v_sqrt_f32_e32 v129, v129
	v_sqrt_f32_e32 v130, v130
	v_sqrt_f32_e32 v131, v131
	s_waitcnt lgkmcnt(0)
	v_lshlrev_b32_e32 v234, 16, v234
	v_lshlrev_b32_e32 v235, 16, v235
	v_lshlrev_b32_e32 v236, 16, v236
	v_lshlrev_b32_e32 v237, 16, v237
	v_lshlrev_b32_e32 v238, 16, v238
	v_lshlrev_b32_e32 v239, 16, v239
	v_lshlrev_b32_e32 v240, 16, v240
	v_lshlrev_b32_e32 v241, 16, v241
	v_pk_mul_f32 v[124:125], v[124:125], v[234:235]
	v_pk_mul_f32 v[126:127], v[126:127], v[236:237]
	v_pk_mul_f32 v[132:133], v[132:133], v[238:239]
	v_pk_mul_f32 v[134:135], v[134:135], v[240:241]
	v_pk_mul_f32 v[124:125], v[124:125], v[120:121]
	v_pk_mul_f32 v[126:127], v[126:127], v[122:123]
	v_pk_mul_f32 v[132:133], v[132:133], v[128:129]
	v_pk_mul_f32 v[134:135], v[134:135], v[130:131]
	v_cvt_pk_bf16_f32 v210, v210, v211
	v_cvt_pk_bf16_f32 v124, v124, v125
	v_cvt_pk_bf16_f32 v212, v212, v213
	v_cvt_pk_bf16_f32 v126, v126, v127
	v_cvt_pk_bf16_f32 v214, v214, v215
	v_cvt_pk_bf16_f32 v132, v132, v133
	v_cvt_pk_bf16_f32 v216, v216, v217
	v_cvt_pk_bf16_f32 v134, v134, v135
	ds_write_b16 v198, v210 offset:12800
	ds_write_b16_d16_hi v198, v210 offset:13200
	ds_write_b16 v199, v124 offset:12800
	ds_write_b16_d16_hi v199, v124 offset:13200
	ds_write_b16 v198, v212 offset:13600
	ds_write_b16_d16_hi v198, v212 offset:14000
	ds_write_b16 v199, v126 offset:13600
	ds_write_b16_d16_hi v199, v126 offset:14000
	ds_write_b16 v198, v214 offset:19200
	ds_write_b16_d16_hi v198, v214 offset:19600
	ds_write_b16 v199, v132 offset:19200
	ds_write_b16_d16_hi v199, v132 offset:19600
	ds_write_b16 v198, v216 offset:20000
	ds_write_b16_d16_hi v198, v216 offset:20400
	ds_write_b16 v199, v134 offset:20000
	ds_write_b16_d16_hi v199, v134 offset:20400
